# speedup vs baseline: 1.0150x; 1.0016x over previous
; template <class Epi> ...
;     ...
;   const int wid = cx.tid >> 6, lane = cx.tid & 63, wr = wid >> 2, wc = wid & 3, fr = lane & 15, fq = lane >> 4;
;   const int wv1k = __builtin_amdgcn_readfirstlane(cx.tid >> 6) * 1024;
;   unsigned so0, so1;
;   { int r, c; stage_rc(cx.tid * 16, r, c); so0 = (unsigned)(r * K + c) * 2u; stage_rc(cx.tid * 16 + 8192, r, c); so1 = (unsigned)(r * K + c) * 2u; }
.LBB0_58:
	s_cmp_eq_u32 s28, 1
	s_mov_b64 s[4:5], -1
	s_cbranch_scc0 .LBB0_69
	s_cmpk_gt_i32 s59, 0x20ff
	s_cbranch_scc1 .LBB0_68
	v_ashrrev_i32_e32 v2, 31, v150
	v_lshrrev_b32_e32 v2, 26, v2
	v_add_u32_e32 v4, v150, v2
	v_bfe_i32 v2, v150, 27, 1
	v_lshlrev_b32_e32 v0, 4, v150
	v_lshrrev_b32_e32 v2, 22, v2
	v_add_u32_e32 v2, v0, v2
	v_and_b32_e32 v2, 0xfffffc00, v2
	v_sub_u32_e32 v2, v0, v2
	v_lshrrev_b32_e32 v3, 4, v2
	v_bitop3_b32 v2, v3, v2, 32 bitop3:0x6c
	v_ashrrev_i32_e32 v6, 31, v2
	v_lshrrev_b32_e32 v6, 26, v6
	v_add_u32_e32 v6, v2, v6
	v_ashrrev_i32_e32 v7, 6, v6
	v_and_b32_e32 v6, 0xc0, v6
	v_ashrrev_i32_e32 v5, 6, v4
	v_sub_u32_e32 v2, v2, v6
	v_mov_b32_e32 v13, 1
	v_lshlrev_b32_e32 v8, 5, v5
	v_ashrrev_i16_sdwa v2, v13, sext(v2) dst_sel:DWORD dst_unused:UNUSED_PAD src0_sel:DWORD src1_sel:BYTE_0
	v_and_b32_e32 v8, 32, v8
	v_bfe_i32 v6, v2, 0, 16
	v_add_u32_e32 v0, 0x2000, v0
	v_add_u32_e32 v2, v8, v6
	v_ashrrev_i32_e32 v8, 31, v0
	v_lshrrev_b32_e32 v8, 22, v8
	v_add_u32_e32 v8, v0, v8
	v_ashrrev_i32_e32 v8, 10, v8
	v_mul_i32_i24_e32 v9, 0x400, v8
	v_sub_u32_e32 v0, v0, v9
	v_lshrrev_b32_e32 v9, 4, v0
	v_bitop3_b32 v0, v9, v0, 32 bitop3:0x6c
	v_ashrrev_i32_e32 v10, 31, v0
	v_lshrrev_b32_e32 v10, 26, v10
	v_add_u32_e32 v10, v0, v10
	v_ashrrev_i32_e32 v11, 6, v10
	v_and_b32_e32 v10, 0xc0, v10
	v_readlane_b32 s4, v255, 41
	v_sub_u32_e32 v0, v0, v10
	v_readlane_b32 s5, v255, 42
	v_lshlrev_b32_e32 v3, 3, v5
	v_ashrrev_i16_sdwa v0, v13, sext(v0) dst_sel:DWORD dst_unused:UNUSED_PAD src0_sel:DWORD src1_sel:BYTE_0
	s_mov_b32 s6, s4
	s_ashr_i32 s7, s4, 31
	v_writelane_b32 v255, s4, 41
	v_bfe_i32 v10, v0, 0, 16
	v_and_b32_e32 v0, 0x1ffff0, v3
	v_writelane_b32 v255, s5, 42
	s_lshl_b64 s[4:5], s[6:7], 6
	v_lshlrev_b32_e32 v9, 3, v8
	v_lshlrev_b32_e32 v12, 5, v8
	v_add_lshl_u32 v0, v7, v0, 11
	s_add_u32 s6, s88, s4
	v_and_b32_e32 v12, 32, v12
	v_lshl_add_u32 v0, v2, 1, v0
	v_and_b32_e32 v2, 0x1ffff0, v9
	s_addc_u32 s7, s89, s5
	v_ashrrev_i32_e32 v151, 6, v150
	v_add_u32_e32 v12, v12, v10
	v_add_lshl_u32 v2, v11, v2, 11
	s_and_b64 s[4:5], s[14:15], exec
	v_and_b32_e32 v14, 15, v150
	v_lshl_add_u32 v130, v12, 1, v2
	v_lshlrev_b32_e32 v2, 12, v151
	v_lshlrev_b32_e32 v3, 2, v150
	s_cselect_b32 s4, 48, 0
	v_and_b32_e32 v15, 48, v150
	v_and_b32_e32 v9, 0x3000, v2
	v_lshlrev_b32_e32 v2, 6, v14
	v_and_b32_e32 v3, 32, v3
	s_add_u32 s4, s6, s4
	v_bitop3_b32 v2, v2, v3, v15 bitop3:0x36
	v_readlane_b32 s6, v255, 21
	v_add_u32_e32 v18, 0, v2
	s_addc_u32 s5, s7, 0
	v_add_u32_e32 v12, s6, v2
	v_readlane_b32 s6, v255, 22
	s_load_dwordx4 s[8:11], s[88:89], 0x168
	s_load_dwordx2 s[18:19], s[4:5], 0xb0
	v_add_u32_e32 v14, s6, v2
	v_readlane_b32 s6, v255, 23
	v_lshlrev_b32_e32 v5, 14, v5
	v_and_b32_e32 v5, 0xffff8000, v5
	v_add_u32_e32 v16, s6, v2
	v_readlane_b32 s6, v255, 24
	v_ashrrev_i32_e32 v13, 8, v150
	v_lshl_add_u32 v5, v7, 11, v5
	v_add_u32_e32 v17, s6, v2
	v_lshlrev_b32_e32 v2, 6, v150
	s_movk_i32 s6, 0x3c0
	v_and_or_b32 v2, v2, s6, v15
	v_xad_u32 v15, v2, v3, 0
	v_lshlrev_b32_e32 v2, 14, v8
	v_and_b32_e32 v2, 0xffff8000, v2
	v_lshl_add_u32 v2, v11, 11, v2
	v_lshlrev_b32_e32 v3, 6, v8
	v_cmp_eq_u32_e64 s[4:5], 1, v13
	v_lshlrev_b32_e32 v13, 13, v13
	v_and_or_b32 v2, v3, 64, v2
	v_and_or_b32 v4, v4, 64, v5
	v_or_b32_e32 v19, 0x800, v13
	v_or_b32_e32 v20, 0x1000, v13
	v_or_b32_e32 v21, 0x1800, v13
	s_movk_i32 s6, 0x100
	v_lshl_add_u32 v2, v10, 1, v2
	v_mov_b32_e32 v3, v1
	v_lshl_add_u32 v4, v6, 1, v4
	v_mov_b32_e32 v5, v1
	v_mov_b32_e32 v131, v1
	v_cmp_gt_u32_e64 s[6:7], s6, v150
	s_waitcnt lgkmcnt(0)
	v_lshl_add_u64 v[132:133], s[8:9], 0, v[2:3]
	v_lshl_add_u64 v[134:135], s[8:9], 0, v[4:5]
	v_lshl_add_u64 v[136:137], s[18:19], 0, v[2:3]
	v_lshl_add_u64 v[138:139], s[18:19], 0, v[4:5]
	v_add_u32_e32 v154, v12, v9
	v_add_u32_e32 v155, v18, v13
	v_add_u32_e32 v156, v15, v19
	v_add_u32_e32 v157, v15, v20
	v_add_u32_e32 v158, v15, v21
	v_add_u32_e32 v159, v14, v9
	v_add_u32_e32 v160, v16, v9
	v_add_u32_e32 v161, v17, v9
	v_readfirstlane_b32 s20, v150
	s_nop 3
	s_lshr_b32 s20, s20, 6
	s_cmp_ge_u32 s20, 4
	s_cbranch_scc1 .Lprio_g1_done
	s_setprio 1

; DEVINL bool run_phase(int ph, int rep) {
;     ...
;       for (int t = cx.bid; t < nwg; t += cx.nb) {
;         int pm, pn; tile_coords(t, nM, nN, pm, pn);
.LBB0_74:
	v_readfirstlane_b32 s100, v234
	s_nop 3
	s_lshr_b32 s100, s100, 6
	s_cmp_ge_u32 s100, 4
	s_cbranch_scc1 .Lprio_74_done
	s_setprio 1
